# v5 + attention O-store epilogue rewritten: DPP neighbour exchange instead of ds_bpermute round trips, 32 full-wave dword stores instead of 64 half-wave stores
# speedup vs baseline: 1.0023x; 1.0023x over previous
.LBB0_1078:
	v_cndmask_b32_e64 v100, v100, v162, s[6:7]
	v_mul_f32_e32 v100, 0xbdd53b94, v100
	v_pk_fma_f32 v[96:97], v[96:97], s[74:75], v[100:101] op_sel_hi:[1,0,0]
	v_pk_fma_f32 v[94:95], v[94:95], s[74:75], v[100:101] op_sel_hi:[1,0,0]
	v_pk_fma_f32 v[92:93], v[92:93], s[74:75], v[100:101] op_sel_hi:[1,0,0]
	v_pk_fma_f32 v[90:91], v[90:91], s[74:75], v[100:101] op_sel_hi:[1,0,0]
	v_pk_fma_f32 v[88:89], v[88:89], s[74:75], v[100:101] op_sel_hi:[1,0,0]
	v_pk_fma_f32 v[86:87], v[86:87], s[74:75], v[100:101] op_sel_hi:[1,0,0]
	v_pk_fma_f32 v[84:85], v[84:85], s[74:75], v[100:101] op_sel_hi:[1,0,0]
	v_pk_fma_f32 v[82:83], v[82:83], s[74:75], v[100:101] op_sel_hi:[1,0,0]
	v_pk_fma_f32 v[80:81], v[80:81], s[74:75], v[100:101] op_sel_hi:[1,0,0]
	v_pk_fma_f32 v[78:79], v[78:79], s[74:75], v[100:101] op_sel_hi:[1,0,0]
	v_pk_fma_f32 v[76:77], v[76:77], s[74:75], v[100:101] op_sel_hi:[1,0,0]
	v_pk_fma_f32 v[74:75], v[74:75], s[74:75], v[100:101] op_sel_hi:[1,0,0]
	v_pk_fma_f32 v[72:73], v[72:73], s[74:75], v[100:101] op_sel_hi:[1,0,0]
	v_pk_fma_f32 v[70:71], v[70:71], s[74:75], v[100:101] op_sel_hi:[1,0,0]
	v_pk_fma_f32 v[68:69], v[68:69], s[74:75], v[100:101] op_sel_hi:[1,0,0]
	v_pk_fma_f32 v[66:67], v[66:67], s[74:75], v[100:101] op_sel_hi:[1,0,0]
	v_exp_f32_e32 v82, v82
	v_exp_f32_e32 v83, v83
	v_exp_f32_e32 v84, v84
	v_exp_f32_e32 v85, v85
	v_exp_f32_e32 v86, v86
	v_exp_f32_e32 v87, v87
	v_exp_f32_e32 v88, v88
	v_exp_f32_e32 v89, v89
	v_exp_f32_e32 v90, v90
	v_exp_f32_e32 v91, v91
	v_exp_f32_e32 v92, v92
	v_exp_f32_e32 v93, v93
	v_exp_f32_e32 v94, v94
	v_exp_f32_e32 v95, v95
	v_exp_f32_e32 v96, v96
	v_exp_f32_e32 v97, v97
	v_exp_f32_e32 v100, v66
	v_exp_f32_e32 v101, v67
	v_exp_f32_e32 v102, v68
	v_exp_f32_e32 v103, v69
	v_exp_f32_e32 v104, v70
	v_exp_f32_e32 v105, v71
	v_exp_f32_e32 v106, v72
	v_exp_f32_e32 v107, v73
	v_exp_f32_e32 v108, v74
	v_exp_f32_e32 v110, v76
	v_exp_f32_e32 v112, v78
	v_exp_f32_e32 v114, v80
	v_exp_f32_e32 v115, v81
	v_exp_f32_e32 v113, v79
	v_exp_f32_e32 v111, v77
	v_exp_f32_e32 v109, v75
	v_pk_add_f32 v[66:67], v[96:97], v[114:115]
	v_pk_add_f32 v[68:69], v[94:95], v[112:113]
	v_pk_add_f32 v[70:71], v[92:93], v[110:111]
	v_pk_add_f32 v[72:73], v[90:91], v[108:109]
	v_pk_add_f32 v[74:75], v[88:89], v[106:107]
	v_pk_add_f32 v[76:77], v[86:87], v[104:105]
	v_pk_add_f32 v[78:79], v[84:85], v[102:103]
	v_pk_add_f32 v[80:81], v[82:83], v[100:101]
	v_add_f32_e32 v78, v78, v79
	v_add_f32_e32 v80, v80, v81
	v_add_f32_e32 v76, v76, v77
	v_add_f32_e32 v74, v74, v75
	v_add_f32_e32 v72, v72, v73
	v_add_f32_e32 v70, v70, v71
	v_add_f32_e32 v68, v68, v69
	v_add_f32_e32 v66, v66, v67
	v_add_f32_e32 v78, v80, v78
	v_add_f32_e32 v74, v76, v74
	v_add_f32_e32 v70, v72, v70
	v_add_f32_e32 v66, v68, v66
	v_add_f32_e32 v74, v78, v74
	v_add_f32_e32 v66, v70, v66
	v_add_f32_e32 v66, v74, v66
	v_mov_b32_e32 v67, v66
	s_nop 1
	v_permlane32_swap_b32_e32 v66, v67
	v_cvt_pk_bf16_f32 v68, v82, v83
	v_cvt_pk_bf16_f32 v69, v84, v85
	v_cvt_pk_bf16_f32 v70, v86, v87
	v_cvt_pk_bf16_f32 v71, v88, v89
	v_cvt_pk_bf16_f32 v72, v90, v91
	v_cvt_pk_bf16_f32 v73, v92, v93
	v_cvt_pk_bf16_f32 v74, v94, v95
	v_cvt_pk_bf16_f32 v75, v96, v97
	v_cvt_pk_bf16_f32 v76, v100, v101
	v_cvt_pk_bf16_f32 v77, v102, v103
	v_cvt_pk_bf16_f32 v78, v104, v105
	v_cvt_pk_bf16_f32 v79, v106, v107
	v_cvt_pk_bf16_f32 v80, v108, v109
	v_cvt_pk_bf16_f32 v81, v110, v111
	v_cvt_pk_bf16_f32 v82, v112, v113
	v_cvt_pk_bf16_f32 v83, v114, v115
	s_nop 0
	v_permlane32_swap_b32_e32 v68, v70
	v_permlane32_swap_b32_e32 v69, v71
	v_permlane32_swap_b32_e32 v72, v74
	v_permlane32_swap_b32_e32 v73, v75
	v_permlane32_swap_b32_e32 v76, v78
	v_permlane32_swap_b32_e32 v77, v79
	v_permlane32_swap_b32_e32 v80, v82
	v_permlane32_swap_b32_e32 v81, v83
	ds_read_b64_tr_b16 v[84:85], v197 offset:0x4000
	ds_read_b64_tr_b16 v[86:87], v197 offset:0x4800
	ds_read_b64_tr_b16 v[88:89], v197 offset:0x5000
	ds_read_b64_tr_b16 v[90:91], v197 offset:0x5800
	ds_read_b64_tr_b16 v[92:93], v197 offset:0x6000
	ds_read_b64_tr_b16 v[94:95], v197 offset:0x6800
	ds_read_b64_tr_b16 v[100:101], v197 offset:0x7000
	ds_read_b64_tr_b16 v[102:103], v197 offset:0x7800
	s_waitcnt lgkmcnt(0)
	s_nop 0
	v_mfma_f32_32x32x16_bf16 v[50:65], v[68:71], v[84:87], v[50:65]
	ds_read_b64_tr_b16 v[84:85], v197 offset:0x4200
	ds_read_b64_tr_b16 v[86:87], v197 offset:0x4a00
	v_mfma_f32_32x32x16_bf16 v[50:65], v[72:75], v[88:91], v[50:65]
	ds_read_b64_tr_b16 v[88:89], v197 offset:0x5200
	ds_read_b64_tr_b16 v[90:91], v197 offset:0x5a00
	v_mfma_f32_32x32x16_bf16 v[50:65], v[76:79], v[92:95], v[50:65]
	ds_read_b64_tr_b16 v[92:93], v197 offset:0x6200
	ds_read_b64_tr_b16 v[94:95], v197 offset:0x6a00
	ds_read_b64_tr_b16 v[104:105], v197 offset:0x7200
	ds_read_b64_tr_b16 v[106:107], v197 offset:0x7a00
	s_waitcnt lgkmcnt(0)
	v_mfma_f32_32x32x16_bf16 v[50:65], v[80:83], v[100:103], v[50:65]
	v_mfma_f32_32x32x16_bf16 v[34:49], v[68:71], v[84:87], v[34:49]
	ds_read_b64_tr_b16 v[84:85], v197 offset:0x4400
	ds_read_b64_tr_b16 v[86:87], v197 offset:0x4c00
	v_mfma_f32_32x32x16_bf16 v[34:49], v[72:75], v[88:91], v[34:49]
	ds_read_b64_tr_b16 v[88:89], v197 offset:0x5400
	ds_read_b64_tr_b16 v[90:91], v197 offset:0x5c00
	v_mfma_f32_32x32x16_bf16 v[34:49], v[76:79], v[92:95], v[34:49]
	ds_read_b64_tr_b16 v[92:93], v197 offset:0x6400
	ds_read_b64_tr_b16 v[94:95], v197 offset:0x6c00
	ds_read_b64_tr_b16 v[100:101], v197 offset:0x7400
	ds_read_b64_tr_b16 v[102:103], v197 offset:0x7c00
	s_waitcnt lgkmcnt(0)
	v_mfma_f32_32x32x16_bf16 v[34:49], v[80:83], v[104:107], v[34:49]
	v_mfma_f32_32x32x16_bf16 v[18:33], v[68:71], v[84:87], v[18:33]
	ds_read_b64_tr_b16 v[84:85], v197 offset:0x4600
	ds_read_b64_tr_b16 v[86:87], v197 offset:0x4e00
	v_mfma_f32_32x32x16_bf16 v[18:33], v[72:75], v[88:91], v[18:33]
	ds_read_b64_tr_b16 v[88:89], v197 offset:0x5600
	ds_read_b64_tr_b16 v[90:91], v197 offset:0x5e00
	v_mfma_f32_32x32x16_bf16 v[18:33], v[76:79], v[92:95], v[18:33]
	ds_read_b64_tr_b16 v[92:93], v197 offset:0x6600
	ds_read_b64_tr_b16 v[94:95], v197 offset:0x6e00
	ds_read_b64_tr_b16 v[104:105], v197 offset:0x7600
	ds_read_b64_tr_b16 v[106:107], v197 offset:0x7e00
	s_waitcnt lgkmcnt(0)
	v_mfma_f32_32x32x16_bf16 v[18:33], v[80:83], v[100:103], v[18:33]
	v_mfma_f32_32x32x16_bf16 v[2:17], v[68:71], v[84:87], v[2:17]
	v_mfma_f32_32x32x16_bf16 v[2:17], v[72:75], v[88:91], v[2:17]
	v_mfma_f32_32x32x16_bf16 v[2:17], v[76:79], v[92:95], v[2:17]
	v_mfma_f32_32x32x16_bf16 v[2:17], v[80:83], v[104:107], v[2:17]
	s_and_saveexec_b64 s[0:1], s[4:5]
	v_add_f32_e32 v0, v0, v98
	v_fmac_f32_e32 v0, v200, v163
	v_add_f32_e32 v66, v66, v67
	v_fmac_f32_e32 v66, v0, v99
	ds_write_b32 v199, v66
	s_or_b64 exec, exec, s[0:1]
	s_waitcnt lgkmcnt(0)
	ds_read_b128 v[78:81], v198
	ds_read_b128 v[74:77], v198 offset:32
	ds_read_b128 v[70:73], v198 offset:64
	ds_read_b128 v[66:69], v198 offset:96
	s_lshl_b64 s[0:1], s[96:97], 12
	v_readlane_b32 s4, v254, 51
	s_nop 3
	s_add_u32 s4, s4, s0
	s_addc_u32 s5, s33, s1
	s_ashr_i32 s89, s88, 31
	s_lshl_b64 s[0:1], s[88:89], 12
	s_add_u32 s0, s4, s0
	s_addc_u32 s1, s5, s1
	v_and_b32_e32 v0, 1, v195
	v_cmp_eq_u32_e64 s[4:5], 0, v0
	v_lshlrev_b32_e32 v0, 1, v194
	v_lshl_add_u64 v[82:83], s[0:1], 0, v[0:1]
	v_lshlrev_b32_e32 v0, 14, v193
	v_lshl_add_u64 v[82:83], v[82:83], 0, v[0:1]
	v_mov_b32_e32 v0, 0xffe
	v_cndmask_b32_e64 v0, v0, 0, s[4:5]
	v_lshl_add_u64 v[82:83], v[82:83], 0, v[0:1]
	s_waitcnt lgkmcnt(0)
	v_rcp_f32_e32 v78, v78
	v_rcp_f32_e32 v79, v79
	v_rcp_f32_e32 v80, v80
	v_rcp_f32_e32 v81, v81
	v_rcp_f32_e32 v74, v74
	v_rcp_f32_e32 v75, v75
	v_rcp_f32_e32 v76, v76
	v_rcp_f32_e32 v77, v77
	v_rcp_f32_e32 v70, v70
	v_rcp_f32_e32 v71, v71
	v_rcp_f32_e32 v72, v72
	v_rcp_f32_e32 v73, v73
	v_rcp_f32_e32 v66, v66
	v_rcp_f32_e32 v67, v67
	v_rcp_f32_e32 v68, v68
	v_rcp_f32_e32 v69, v69
	s_nop 0
	v_mul_f32_e32 v50, v50, v78
	v_mul_f32_e32 v51, v51, v79
	v_mul_f32_e32 v34, v34, v78
	v_mul_f32_e32 v35, v35, v79
	v_mul_f32_e32 v18, v18, v78
	v_mul_f32_e32 v19, v19, v79
	v_mul_f32_e32 v2, v2, v78
	v_mul_f32_e32 v3, v3, v79
	v_cndmask_b32_e64 v84, v50, v51, s[4:5]
	v_cndmask_b32_e64 v85, v34, v35, s[4:5]
	v_cndmask_b32_e64 v86, v18, v19, s[4:5]
	v_cndmask_b32_e64 v87, v2, v3, s[4:5]
	v_mov_b32_dpp v88, v84 quad_perm:[1,0,3,2] row_mask:0xf bank_mask:0xf
	v_mov_b32_dpp v89, v85 quad_perm:[1,0,3,2] row_mask:0xf bank_mask:0xf
	v_mov_b32_dpp v90, v86 quad_perm:[1,0,3,2] row_mask:0xf bank_mask:0xf
	v_mov_b32_dpp v91, v87 quad_perm:[1,0,3,2] row_mask:0xf bank_mask:0xf
	v_cndmask_b32_e64 v92, v88, v50, s[4:5]
	v_cndmask_b32_e64 v96, v51, v88, s[4:5]
	v_cndmask_b32_e64 v93, v89, v34, s[4:5]
	v_cndmask_b32_e64 v97, v35, v89, s[4:5]
	v_cndmask_b32_e64 v94, v90, v18, s[4:5]
	v_cndmask_b32_e64 v98, v19, v90, s[4:5]
	v_cndmask_b32_e64 v95, v91, v2, s[4:5]
	v_cndmask_b32_e64 v99, v3, v91, s[4:5]
	v_cvt_pk_bf16_f32 v100, v92, v96
	v_cvt_pk_bf16_f32 v101, v93, v97
	v_cvt_pk_bf16_f32 v102, v94, v98
	v_cvt_pk_bf16_f32 v103, v95, v99
	global_store_dword v[82:83], v100, off
	global_store_dword v[82:83], v101, off offset:64
	global_store_dword v[82:83], v102, off offset:128
	global_store_dword v[82:83], v103, off offset:192
	s_mov_b64 s[0:1], 0x2000
	v_lshl_add_u64 v[104:105], v[82:83], 0, s[0:1]
	v_mul_f32_e32 v52, v52, v80
	v_mul_f32_e32 v53, v53, v81
	v_mul_f32_e32 v36, v36, v80
	v_mul_f32_e32 v37, v37, v81
	v_mul_f32_e32 v20, v20, v80
	v_mul_f32_e32 v21, v21, v81
	v_mul_f32_e32 v4, v4, v80
	v_mul_f32_e32 v5, v5, v81
	v_cndmask_b32_e64 v84, v52, v53, s[4:5]
	v_cndmask_b32_e64 v85, v36, v37, s[4:5]
	v_cndmask_b32_e64 v86, v20, v21, s[4:5]
	v_cndmask_b32_e64 v87, v4, v5, s[4:5]
	v_mov_b32_dpp v88, v84 quad_perm:[1,0,3,2] row_mask:0xf bank_mask:0xf
	v_mov_b32_dpp v89, v85 quad_perm:[1,0,3,2] row_mask:0xf bank_mask:0xf
	v_mov_b32_dpp v90, v86 quad_perm:[1,0,3,2] row_mask:0xf bank_mask:0xf
	v_mov_b32_dpp v91, v87 quad_perm:[1,0,3,2] row_mask:0xf bank_mask:0xf
	v_cndmask_b32_e64 v92, v88, v52, s[4:5]
	v_cndmask_b32_e64 v96, v53, v88, s[4:5]
	v_cndmask_b32_e64 v93, v89, v36, s[4:5]
	v_cndmask_b32_e64 v97, v37, v89, s[4:5]
	v_cndmask_b32_e64 v94, v90, v20, s[4:5]
	v_cndmask_b32_e64 v98, v21, v90, s[4:5]
	v_cndmask_b32_e64 v95, v91, v4, s[4:5]
	v_cndmask_b32_e64 v99, v5, v91, s[4:5]
	v_cvt_pk_bf16_f32 v100, v92, v96
	v_cvt_pk_bf16_f32 v101, v93, v97
	v_cvt_pk_bf16_f32 v102, v94, v98
	v_cvt_pk_bf16_f32 v103, v95, v99
	global_store_dword v[104:105], v100, off
	global_store_dword v[104:105], v101, off offset:64
	global_store_dword v[104:105], v102, off offset:128
	global_store_dword v[104:105], v103, off offset:192
	s_mov_b64 s[0:1], 0x8000
	v_lshl_add_u64 v[104:105], v[82:83], 0, s[0:1]
	v_mul_f32_e32 v54, v54, v74
	v_mul_f32_e32 v55, v55, v75
	v_mul_f32_e32 v38, v38, v74
	v_mul_f32_e32 v39, v39, v75
	v_mul_f32_e32 v22, v22, v74
	v_mul_f32_e32 v23, v23, v75
	v_mul_f32_e32 v6, v6, v74
	v_mul_f32_e32 v7, v7, v75
	v_cndmask_b32_e64 v84, v54, v55, s[4:5]
	v_cndmask_b32_e64 v85, v38, v39, s[4:5]
	v_cndmask_b32_e64 v86, v22, v23, s[4:5]
	v_cndmask_b32_e64 v87, v6, v7, s[4:5]
	v_mov_b32_dpp v88, v84 quad_perm:[1,0,3,2] row_mask:0xf bank_mask:0xf
	v_mov_b32_dpp v89, v85 quad_perm:[1,0,3,2] row_mask:0xf bank_mask:0xf
	v_mov_b32_dpp v90, v86 quad_perm:[1,0,3,2] row_mask:0xf bank_mask:0xf
	v_mov_b32_dpp v91, v87 quad_perm:[1,0,3,2] row_mask:0xf bank_mask:0xf
	v_cndmask_b32_e64 v92, v88, v54, s[4:5]
	v_cndmask_b32_e64 v96, v55, v88, s[4:5]
	v_cndmask_b32_e64 v93, v89, v38, s[4:5]
	v_cndmask_b32_e64 v97, v39, v89, s[4:5]
	v_cndmask_b32_e64 v94, v90, v22, s[4:5]
	v_cndmask_b32_e64 v98, v23, v90, s[4:5]
	v_cndmask_b32_e64 v95, v91, v6, s[4:5]
	v_cndmask_b32_e64 v99, v7, v91, s[4:5]
	v_cvt_pk_bf16_f32 v100, v92, v96
	v_cvt_pk_bf16_f32 v101, v93, v97
	v_cvt_pk_bf16_f32 v102, v94, v98
	v_cvt_pk_bf16_f32 v103, v95, v99
	global_store_dword v[104:105], v100, off
	global_store_dword v[104:105], v101, off offset:64
	global_store_dword v[104:105], v102, off offset:128
	global_store_dword v[104:105], v103, off offset:192
	s_mov_b64 s[0:1], 0xa000
	v_lshl_add_u64 v[104:105], v[82:83], 0, s[0:1]
	v_mul_f32_e32 v56, v56, v76
	v_mul_f32_e32 v57, v57, v77
	v_mul_f32_e32 v40, v40, v76
	v_mul_f32_e32 v41, v41, v77
	v_mul_f32_e32 v24, v24, v76
	v_mul_f32_e32 v25, v25, v77
	v_mul_f32_e32 v8, v8, v76
	v_mul_f32_e32 v9, v9, v77
	v_cndmask_b32_e64 v84, v56, v57, s[4:5]
	v_cndmask_b32_e64 v85, v40, v41, s[4:5]
	v_cndmask_b32_e64 v86, v24, v25, s[4:5]
	v_cndmask_b32_e64 v87, v8, v9, s[4:5]
	v_mov_b32_dpp v88, v84 quad_perm:[1,0,3,2] row_mask:0xf bank_mask:0xf
	v_mov_b32_dpp v89, v85 quad_perm:[1,0,3,2] row_mask:0xf bank_mask:0xf
	v_mov_b32_dpp v90, v86 quad_perm:[1,0,3,2] row_mask:0xf bank_mask:0xf
	v_mov_b32_dpp v91, v87 quad_perm:[1,0,3,2] row_mask:0xf bank_mask:0xf
	v_cndmask_b32_e64 v92, v88, v56, s[4:5]
	v_cndmask_b32_e64 v96, v57, v88, s[4:5]
	v_cndmask_b32_e64 v93, v89, v40, s[4:5]
	v_cndmask_b32_e64 v97, v41, v89, s[4:5]
	v_cndmask_b32_e64 v94, v90, v24, s[4:5]
	v_cndmask_b32_e64 v98, v25, v90, s[4:5]
	v_cndmask_b32_e64 v95, v91, v8, s[4:5]
	v_cndmask_b32_e64 v99, v9, v91, s[4:5]
	v_cvt_pk_bf16_f32 v100, v92, v96
	v_cvt_pk_bf16_f32 v101, v93, v97
	v_cvt_pk_bf16_f32 v102, v94, v98
	v_cvt_pk_bf16_f32 v103, v95, v99
	global_store_dword v[104:105], v100, off
	global_store_dword v[104:105], v101, off offset:64
	global_store_dword v[104:105], v102, off offset:128
	global_store_dword v[104:105], v103, off offset:192
	s_mov_b64 s[0:1], 0x10000
	v_lshl_add_u64 v[104:105], v[82:83], 0, s[0:1]
	v_mul_f32_e32 v58, v58, v70
	v_mul_f32_e32 v59, v59, v71
	v_mul_f32_e32 v42, v42, v70
	v_mul_f32_e32 v43, v43, v71
	v_mul_f32_e32 v26, v26, v70
	v_mul_f32_e32 v27, v27, v71
	v_mul_f32_e32 v10, v10, v70
	v_mul_f32_e32 v11, v11, v71
	v_cndmask_b32_e64 v84, v58, v59, s[4:5]
	v_cndmask_b32_e64 v85, v42, v43, s[4:5]
	v_cndmask_b32_e64 v86, v26, v27, s[4:5]
	v_cndmask_b32_e64 v87, v10, v11, s[4:5]
	v_mov_b32_dpp v88, v84 quad_perm:[1,0,3,2] row_mask:0xf bank_mask:0xf
	v_mov_b32_dpp v89, v85 quad_perm:[1,0,3,2] row_mask:0xf bank_mask:0xf
	v_mov_b32_dpp v90, v86 quad_perm:[1,0,3,2] row_mask:0xf bank_mask:0xf
	v_mov_b32_dpp v91, v87 quad_perm:[1,0,3,2] row_mask:0xf bank_mask:0xf
	v_cndmask_b32_e64 v92, v88, v58, s[4:5]
	v_cndmask_b32_e64 v96, v59, v88, s[4:5]
	v_cndmask_b32_e64 v93, v89, v42, s[4:5]
	v_cndmask_b32_e64 v97, v43, v89, s[4:5]
	v_cndmask_b32_e64 v94, v90, v26, s[4:5]
	v_cndmask_b32_e64 v98, v27, v90, s[4:5]
	v_cndmask_b32_e64 v95, v91, v10, s[4:5]
	v_cndmask_b32_e64 v99, v11, v91, s[4:5]
	v_cvt_pk_bf16_f32 v100, v92, v96
	v_cvt_pk_bf16_f32 v101, v93, v97
	v_cvt_pk_bf16_f32 v102, v94, v98
	v_cvt_pk_bf16_f32 v103, v95, v99
	global_store_dword v[104:105], v100, off
	global_store_dword v[104:105], v101, off offset:64
	global_store_dword v[104:105], v102, off offset:128
	global_store_dword v[104:105], v103, off offset:192
	s_mov_b64 s[0:1], 0x12000
	v_lshl_add_u64 v[104:105], v[82:83], 0, s[0:1]
	v_mul_f32_e32 v60, v60, v72
	v_mul_f32_e32 v61, v61, v73
	v_mul_f32_e32 v44, v44, v72
	v_mul_f32_e32 v45, v45, v73
	v_mul_f32_e32 v28, v28, v72
	v_mul_f32_e32 v29, v29, v73
	v_mul_f32_e32 v12, v12, v72
	v_mul_f32_e32 v13, v13, v73
	v_cndmask_b32_e64 v84, v60, v61, s[4:5]
	v_cndmask_b32_e64 v85, v44, v45, s[4:5]
	v_cndmask_b32_e64 v86, v28, v29, s[4:5]
	v_cndmask_b32_e64 v87, v12, v13, s[4:5]
	v_mov_b32_dpp v88, v84 quad_perm:[1,0,3,2] row_mask:0xf bank_mask:0xf
	v_mov_b32_dpp v89, v85 quad_perm:[1,0,3,2] row_mask:0xf bank_mask:0xf
	v_mov_b32_dpp v90, v86 quad_perm:[1,0,3,2] row_mask:0xf bank_mask:0xf
	v_mov_b32_dpp v91, v87 quad_perm:[1,0,3,2] row_mask:0xf bank_mask:0xf
	v_cndmask_b32_e64 v92, v88, v60, s[4:5]
	v_cndmask_b32_e64 v96, v61, v88, s[4:5]
	v_cndmask_b32_e64 v93, v89, v44, s[4:5]
	v_cndmask_b32_e64 v97, v45, v89, s[4:5]
	v_cndmask_b32_e64 v94, v90, v28, s[4:5]
	v_cndmask_b32_e64 v98, v29, v90, s[4:5]
	v_cndmask_b32_e64 v95, v91, v12, s[4:5]
	v_cndmask_b32_e64 v99, v13, v91, s[4:5]
	v_cvt_pk_bf16_f32 v100, v92, v96
	v_cvt_pk_bf16_f32 v101, v93, v97
	v_cvt_pk_bf16_f32 v102, v94, v98
	v_cvt_pk_bf16_f32 v103, v95, v99
	global_store_dword v[104:105], v100, off
	global_store_dword v[104:105], v101, off offset:64
	global_store_dword v[104:105], v102, off offset:128
	global_store_dword v[104:105], v103, off offset:192
	s_mov_b64 s[0:1], 0x18000
	v_lshl_add_u64 v[104:105], v[82:83], 0, s[0:1]
	v_mul_f32_e32 v62, v62, v66
	v_mul_f32_e32 v63, v63, v67
	v_mul_f32_e32 v46, v46, v66
	v_mul_f32_e32 v47, v47, v67
	v_mul_f32_e32 v30, v30, v66
	v_mul_f32_e32 v31, v31, v67
	v_mul_f32_e32 v14, v14, v66
	v_mul_f32_e32 v15, v15, v67
	v_cndmask_b32_e64 v84, v62, v63, s[4:5]
	v_cndmask_b32_e64 v85, v46, v47, s[4:5]
	v_cndmask_b32_e64 v86, v30, v31, s[4:5]
	v_cndmask_b32_e64 v87, v14, v15, s[4:5]
	v_mov_b32_dpp v88, v84 quad_perm:[1,0,3,2] row_mask:0xf bank_mask:0xf
	v_mov_b32_dpp v89, v85 quad_perm:[1,0,3,2] row_mask:0xf bank_mask:0xf
	v_mov_b32_dpp v90, v86 quad_perm:[1,0,3,2] row_mask:0xf bank_mask:0xf
	v_mov_b32_dpp v91, v87 quad_perm:[1,0,3,2] row_mask:0xf bank_mask:0xf
	v_cndmask_b32_e64 v92, v88, v62, s[4:5]
	v_cndmask_b32_e64 v96, v63, v88, s[4:5]
	v_cndmask_b32_e64 v93, v89, v46, s[4:5]
	v_cndmask_b32_e64 v97, v47, v89, s[4:5]
	v_cndmask_b32_e64 v94, v90, v30, s[4:5]
	v_cndmask_b32_e64 v98, v31, v90, s[4:5]
	v_cndmask_b32_e64 v95, v91, v14, s[4:5]
	v_cndmask_b32_e64 v99, v15, v91, s[4:5]
	v_cvt_pk_bf16_f32 v100, v92, v96
	v_cvt_pk_bf16_f32 v101, v93, v97
	v_cvt_pk_bf16_f32 v102, v94, v98
	v_cvt_pk_bf16_f32 v103, v95, v99
	global_store_dword v[104:105], v100, off
	global_store_dword v[104:105], v101, off offset:64
	global_store_dword v[104:105], v102, off offset:128
	global_store_dword v[104:105], v103, off offset:192
	s_mov_b64 s[0:1], 0x1a000
	v_lshl_add_u64 v[104:105], v[82:83], 0, s[0:1]
	v_mul_f32_e32 v64, v64, v68
	v_mul_f32_e32 v65, v65, v69
	v_mul_f32_e32 v48, v48, v68
	v_mul_f32_e32 v49, v49, v69
	v_mul_f32_e32 v32, v32, v68
	v_mul_f32_e32 v33, v33, v69
	v_mul_f32_e32 v16, v16, v68
	v_mul_f32_e32 v17, v17, v69
	v_cndmask_b32_e64 v84, v64, v65, s[4:5]
	v_cndmask_b32_e64 v85, v48, v49, s[4:5]
	v_cndmask_b32_e64 v86, v32, v33, s[4:5]
	v_cndmask_b32_e64 v87, v16, v17, s[4:5]
	v_mov_b32_dpp v88, v84 quad_perm:[1,0,3,2] row_mask:0xf bank_mask:0xf
	v_mov_b32_dpp v89, v85 quad_perm:[1,0,3,2] row_mask:0xf bank_mask:0xf
	v_mov_b32_dpp v90, v86 quad_perm:[1,0,3,2] row_mask:0xf bank_mask:0xf
	v_mov_b32_dpp v91, v87 quad_perm:[1,0,3,2] row_mask:0xf bank_mask:0xf
	v_cndmask_b32_e64 v92, v88, v64, s[4:5]
	v_cndmask_b32_e64 v96, v65, v88, s[4:5]
	v_cndmask_b32_e64 v93, v89, v48, s[4:5]
	v_cndmask_b32_e64 v97, v49, v89, s[4:5]
	v_cndmask_b32_e64 v94, v90, v32, s[4:5]
	v_cndmask_b32_e64 v98, v33, v90, s[4:5]
	v_cndmask_b32_e64 v95, v91, v16, s[4:5]
	v_cndmask_b32_e64 v99, v17, v91, s[4:5]
	v_cvt_pk_bf16_f32 v100, v92, v96
	v_cvt_pk_bf16_f32 v101, v93, v97
	v_cvt_pk_bf16_f32 v102, v94, v98
	v_cvt_pk_bf16_f32 v103, v95, v99
	global_store_dword v[104:105], v100, off
	global_store_dword v[104:105], v101, off offset:64
	global_store_dword v[104:105], v102, off offset:128
	global_store_dword v[104:105], v103, off offset:192
	s_branch .LBB0_1050
